# HG_H2 chunk-state scan software-pipelined (group prefetch, counted vmcnt) on top of MIX_O block-id rotation
# speedup vs baseline: 1.0191x; 1.0003x over previous
; __device__ __forceinline__ void hgrn_h2(const int e) {
;     ...
;     for (int gid = bid * 512 + tid; gid < 16 * 128 * 64; gid += gsz * 512) {
;         const int bh = gid >> 13, k = (gid >> 6) & 127, v2 = (gid & 63) * 2;
;         f32x2h S = (f32x2h){0.f, 0.f};
;         float* ptr = LBUF + (size_t)bh * 64 * 16384 + (size_t)k * 128 + v2; const float* dp = DTOT + (size_t)bh * 64 * 128 + k;
; #pragma unroll 8
;         for (int c = 0; c < 64; ++c) { const f32x2h t = *(const f32x2h*)(ptr + (size_t)c * 16384); const float d = dp[c * 128]; *(f32x2h*)(ptr + (size_t)c * 16384) = S; S = S * d + t; }
.LBB0_893:
	s_waitcnt lgkmcnt(0)
	s_add_u32 s12, s8, 0x2b200000
	s_addc_u32 s13, s9, 0
	s_mov_b32 s100, s12
	s_mov_b32 s101, s13
	s_add_u32 s14, s8, 0x2f200000
	s_addc_u32 s15, s9, 0
	global_load_dwordx2 v[24:25], v4, s[12:13]
	s_add_u32 s12, s12, 0x10000
	s_addc_u32 s13, s13, 0
	global_load_dword v56, v6, s[14:15] offset:0
	global_load_dwordx2 v[26:27], v4, s[12:13]
	s_add_u32 s12, s12, 0x10000
	s_addc_u32 s13, s13, 0
	global_load_dword v58, v6, s[14:15] offset:512
	global_load_dwordx2 v[28:29], v4, s[12:13]
	s_add_u32 s12, s12, 0x10000
	s_addc_u32 s13, s13, 0
	global_load_dword v60, v6, s[14:15] offset:1024
	global_load_dwordx2 v[30:31], v4, s[12:13]
	s_add_u32 s12, s12, 0x10000
	s_addc_u32 s13, s13, 0
	global_load_dword v62, v6, s[14:15] offset:1536
	global_load_dwordx2 v[32:33], v4, s[12:13]
	s_add_u32 s12, s12, 0x10000
	s_addc_u32 s13, s13, 0
	global_load_dword v64, v6, s[14:15] offset:2048
	global_load_dwordx2 v[34:35], v4, s[12:13]
	s_add_u32 s12, s12, 0x10000
	s_addc_u32 s13, s13, 0
	global_load_dword v66, v6, s[14:15] offset:2560
	global_load_dwordx2 v[36:37], v4, s[12:13]
	s_add_u32 s12, s12, 0x10000
	s_addc_u32 s13, s13, 0
	global_load_dword v68, v6, s[14:15] offset:3072
	global_load_dwordx2 v[38:39], v4, s[12:13]
	s_add_u32 s12, s12, 0x10000
	s_addc_u32 s13, s13, 0
	global_load_dword v70, v6, s[14:15] offset:3584
	s_add_u32 s14, s14, 0x1000
	s_addc_u32 s15, s15, 0
	global_load_dwordx2 v[40:41], v4, s[12:13]
	s_add_u32 s12, s12, 0x10000
	s_addc_u32 s13, s13, 0
	global_load_dword v72, v6, s[14:15] offset:0
	global_load_dwordx2 v[42:43], v4, s[12:13]
	s_add_u32 s12, s12, 0x10000
	s_addc_u32 s13, s13, 0
	global_load_dword v74, v6, s[14:15] offset:512
	global_load_dwordx2 v[44:45], v4, s[12:13]
	s_add_u32 s12, s12, 0x10000
	s_addc_u32 s13, s13, 0
	global_load_dword v76, v6, s[14:15] offset:1024
	global_load_dwordx2 v[46:47], v4, s[12:13]
	s_add_u32 s12, s12, 0x10000
	s_addc_u32 s13, s13, 0
	global_load_dword v78, v6, s[14:15] offset:1536
	global_load_dwordx2 v[48:49], v4, s[12:13]
	s_add_u32 s12, s12, 0x10000
	s_addc_u32 s13, s13, 0
	global_load_dword v80, v6, s[14:15] offset:2048
	global_load_dwordx2 v[50:51], v4, s[12:13]
	s_add_u32 s12, s12, 0x10000
	s_addc_u32 s13, s13, 0
	global_load_dword v82, v6, s[14:15] offset:2560
	global_load_dwordx2 v[52:53], v4, s[12:13]
	s_add_u32 s12, s12, 0x10000
	s_addc_u32 s13, s13, 0
	global_load_dword v84, v6, s[14:15] offset:3072
	global_load_dwordx2 v[54:55], v4, s[12:13]
	s_add_u32 s12, s12, 0x10000
	s_addc_u32 s13, s13, 0
	global_load_dword v86, v6, s[14:15] offset:3584
	s_add_u32 s14, s14, 0x1000
	s_addc_u32 s15, s15, 0
	s_waitcnt vmcnt(30)
	global_store_dwordx2 v4, v[12:13], s[100:101]
	s_add_u32 s100, s100, 0x10000
	s_addc_u32 s101, s101, 0
	v_pk_fma_f32 v[88:89], v[12:13], v[56:57], v[24:25] op_sel_hi:[1,0,1]
	s_waitcnt vmcnt(29)
	global_store_dwordx2 v4, v[88:89], s[100:101]
	s_add_u32 s100, s100, 0x10000
	s_addc_u32 s101, s101, 0
	v_pk_fma_f32 v[12:13], v[88:89], v[58:59], v[26:27] op_sel_hi:[1,0,1]
	s_waitcnt vmcnt(28)
	global_store_dwordx2 v4, v[12:13], s[100:101]
	s_add_u32 s100, s100, 0x10000
	s_addc_u32 s101, s101, 0
	v_pk_fma_f32 v[88:89], v[12:13], v[60:61], v[28:29] op_sel_hi:[1,0,1]
	s_waitcnt vmcnt(27)
	global_store_dwordx2 v4, v[88:89], s[100:101]
	s_add_u32 s100, s100, 0x10000
	s_addc_u32 s101, s101, 0
	v_pk_fma_f32 v[12:13], v[88:89], v[62:63], v[30:31] op_sel_hi:[1,0,1]
	s_waitcnt vmcnt(26)
	global_store_dwordx2 v4, v[12:13], s[100:101]
	s_add_u32 s100, s100, 0x10000
	s_addc_u32 s101, s101, 0
	v_pk_fma_f32 v[88:89], v[12:13], v[64:65], v[32:33] op_sel_hi:[1,0,1]
	s_waitcnt vmcnt(25)
	global_store_dwordx2 v4, v[88:89], s[100:101]
	s_add_u32 s100, s100, 0x10000
	s_addc_u32 s101, s101, 0
	v_pk_fma_f32 v[12:13], v[88:89], v[66:67], v[34:35] op_sel_hi:[1,0,1]
	s_waitcnt vmcnt(24)
	global_store_dwordx2 v4, v[12:13], s[100:101]
	s_add_u32 s100, s100, 0x10000
	s_addc_u32 s101, s101, 0
	v_pk_fma_f32 v[88:89], v[12:13], v[68:69], v[36:37] op_sel_hi:[1,0,1]
	s_waitcnt vmcnt(23)
	global_store_dwordx2 v4, v[88:89], s[100:101]
	s_add_u32 s100, s100, 0x10000
	s_addc_u32 s101, s101, 0
	v_pk_fma_f32 v[12:13], v[88:89], v[70:71], v[38:39] op_sel_hi:[1,0,1]
	global_load_dwordx2 v[24:25], v4, s[12:13]
	s_add_u32 s12, s12, 0x10000
	s_addc_u32 s13, s13, 0
	global_load_dword v56, v6, s[14:15] offset:0
	global_load_dwordx2 v[26:27], v4, s[12:13]
	s_add_u32 s12, s12, 0x10000
	s_addc_u32 s13, s13, 0
	global_load_dword v58, v6, s[14:15] offset:512
	global_load_dwordx2 v[28:29], v4, s[12:13]
	s_add_u32 s12, s12, 0x10000
	s_addc_u32 s13, s13, 0
	global_load_dword v60, v6, s[14:15] offset:1024
	global_load_dwordx2 v[30:31], v4, s[12:13]
	s_add_u32 s12, s12, 0x10000
	s_addc_u32 s13, s13, 0
	global_load_dword v62, v6, s[14:15] offset:1536
	global_load_dwordx2 v[32:33], v4, s[12:13]
	s_add_u32 s12, s12, 0x10000
	s_addc_u32 s13, s13, 0
	global_load_dword v64, v6, s[14:15] offset:2048
	global_load_dwordx2 v[34:35], v4, s[12:13]
	s_add_u32 s12, s12, 0x10000
	s_addc_u32 s13, s13, 0
	global_load_dword v66, v6, s[14:15] offset:2560
	global_load_dwordx2 v[36:37], v4, s[12:13]
	s_add_u32 s12, s12, 0x10000
	s_addc_u32 s13, s13, 0
	global_load_dword v68, v6, s[14:15] offset:3072
	global_load_dwordx2 v[38:39], v4, s[12:13]
	s_add_u32 s12, s12, 0x10000
	s_addc_u32 s13, s13, 0
	global_load_dword v70, v6, s[14:15] offset:3584
	s_add_u32 s14, s14, 0x1000
	s_addc_u32 s15, s15, 0
	s_waitcnt vmcnt(38)
	global_store_dwordx2 v4, v[12:13], s[100:101]
	s_add_u32 s100, s100, 0x10000
	s_addc_u32 s101, s101, 0
	v_pk_fma_f32 v[88:89], v[12:13], v[72:73], v[40:41] op_sel_hi:[1,0,1]
	s_waitcnt vmcnt(37)
; __device__ __forceinline__ void hgrn_h2(const int e) {
;     ...
;     for (int gid = bid * 512 + tid; gid < 16 * 128 * 64; gid += gsz * 512) {
;         const int bh = gid >> 13, k = (gid >> 6) & 127, v2 = (gid & 63) * 2;
;         f32x2h S = (f32x2h){0.f, 0.f};
;         float* ptr = LBUF + (size_t)bh * 64 * 16384 + (size_t)k * 128 + v2; const float* dp = DTOT + (size_t)bh * 64 * 128 + k;
; #pragma unroll 8
;         for (int c = 0; c < 64; ++c) { const f32x2h t = *(const f32x2h*)(ptr + (size_t)c * 16384); const float d = dp[c * 128]; *(f32x2h*)(ptr + (size_t)c * 16384) = S; S = S * d + t; }
	global_store_dwordx2 v4, v[88:89], s[100:101]
	s_add_u32 s100, s100, 0x10000
	s_addc_u32 s101, s101, 0
	v_pk_fma_f32 v[12:13], v[88:89], v[74:75], v[42:43] op_sel_hi:[1,0,1]
	s_waitcnt vmcnt(36)
	global_store_dwordx2 v4, v[12:13], s[100:101]
	s_add_u32 s100, s100, 0x10000
	s_addc_u32 s101, s101, 0
	v_pk_fma_f32 v[88:89], v[12:13], v[76:77], v[44:45] op_sel_hi:[1,0,1]
	s_waitcnt vmcnt(35)
	global_store_dwordx2 v4, v[88:89], s[100:101]
	s_add_u32 s100, s100, 0x10000
	s_addc_u32 s101, s101, 0
	v_pk_fma_f32 v[12:13], v[88:89], v[78:79], v[46:47] op_sel_hi:[1,0,1]
	s_waitcnt vmcnt(34)
	global_store_dwordx2 v4, v[12:13], s[100:101]
	s_add_u32 s100, s100, 0x10000
	s_addc_u32 s101, s101, 0
	v_pk_fma_f32 v[88:89], v[12:13], v[80:81], v[48:49] op_sel_hi:[1,0,1]
	s_waitcnt vmcnt(33)
	global_store_dwordx2 v4, v[88:89], s[100:101]
	s_add_u32 s100, s100, 0x10000
	s_addc_u32 s101, s101, 0
	v_pk_fma_f32 v[12:13], v[88:89], v[82:83], v[50:51] op_sel_hi:[1,0,1]
	s_waitcnt vmcnt(32)
	global_store_dwordx2 v4, v[12:13], s[100:101]
	s_add_u32 s100, s100, 0x10000
	s_addc_u32 s101, s101, 0
	v_pk_fma_f32 v[88:89], v[12:13], v[84:85], v[52:53] op_sel_hi:[1,0,1]
	s_waitcnt vmcnt(31)
	global_store_dwordx2 v4, v[88:89], s[100:101]
	s_add_u32 s100, s100, 0x10000
	s_addc_u32 s101, s101, 0
	v_pk_fma_f32 v[12:13], v[88:89], v[86:87], v[54:55] op_sel_hi:[1,0,1]
	global_load_dwordx2 v[40:41], v4, s[12:13]
	s_add_u32 s12, s12, 0x10000
	s_addc_u32 s13, s13, 0
	global_load_dword v72, v6, s[14:15] offset:0
	global_load_dwordx2 v[42:43], v4, s[12:13]
	s_add_u32 s12, s12, 0x10000
	s_addc_u32 s13, s13, 0
	global_load_dword v74, v6, s[14:15] offset:512
	global_load_dwordx2 v[44:45], v4, s[12:13]
	s_add_u32 s12, s12, 0x10000
	s_addc_u32 s13, s13, 0
	global_load_dword v76, v6, s[14:15] offset:1024
	global_load_dwordx2 v[46:47], v4, s[12:13]
	s_add_u32 s12, s12, 0x10000
	s_addc_u32 s13, s13, 0
	global_load_dword v78, v6, s[14:15] offset:1536
	global_load_dwordx2 v[48:49], v4, s[12:13]
	s_add_u32 s12, s12, 0x10000
	s_addc_u32 s13, s13, 0
	global_load_dword v80, v6, s[14:15] offset:2048
	global_load_dwordx2 v[50:51], v4, s[12:13]
	s_add_u32 s12, s12, 0x10000
	s_addc_u32 s13, s13, 0
	global_load_dword v82, v6, s[14:15] offset:2560
	global_load_dwordx2 v[52:53], v4, s[12:13]
	s_add_u32 s12, s12, 0x10000
	s_addc_u32 s13, s13, 0
	global_load_dword v84, v6, s[14:15] offset:3072
	global_load_dwordx2 v[54:55], v4, s[12:13]
	s_add_u32 s12, s12, 0x10000
	s_addc_u32 s13, s13, 0
	global_load_dword v86, v6, s[14:15] offset:3584
	s_add_u32 s14, s14, 0x1000
	s_addc_u32 s15, s15, 0
	s_waitcnt vmcnt(38)
	global_store_dwordx2 v4, v[12:13], s[100:101]
	s_add_u32 s100, s100, 0x10000
	s_addc_u32 s101, s101, 0
	v_pk_fma_f32 v[88:89], v[12:13], v[56:57], v[24:25] op_sel_hi:[1,0,1]
	s_waitcnt vmcnt(37)
	global_store_dwordx2 v4, v[88:89], s[100:101]
	s_add_u32 s100, s100, 0x10000
	s_addc_u32 s101, s101, 0
	v_pk_fma_f32 v[12:13], v[88:89], v[58:59], v[26:27] op_sel_hi:[1,0,1]
	s_waitcnt vmcnt(36)
	global_store_dwordx2 v4, v[12:13], s[100:101]
	s_add_u32 s100, s100, 0x10000
	s_addc_u32 s101, s101, 0
	v_pk_fma_f32 v[88:89], v[12:13], v[60:61], v[28:29] op_sel_hi:[1,0,1]
	s_waitcnt vmcnt(35)
	global_store_dwordx2 v4, v[88:89], s[100:101]
	s_add_u32 s100, s100, 0x10000
	s_addc_u32 s101, s101, 0
	v_pk_fma_f32 v[12:13], v[88:89], v[62:63], v[30:31] op_sel_hi:[1,0,1]
	s_waitcnt vmcnt(34)
	global_store_dwordx2 v4, v[12:13], s[100:101]
	s_add_u32 s100, s100, 0x10000
	s_addc_u32 s101, s101, 0
	v_pk_fma_f32 v[88:89], v[12:13], v[64:65], v[32:33] op_sel_hi:[1,0,1]
	s_waitcnt vmcnt(33)
	global_store_dwordx2 v4, v[88:89], s[100:101]
	s_add_u32 s100, s100, 0x10000
	s_addc_u32 s101, s101, 0
	v_pk_fma_f32 v[12:13], v[88:89], v[66:67], v[34:35] op_sel_hi:[1,0,1]
	s_waitcnt vmcnt(32)
	global_store_dwordx2 v4, v[12:13], s[100:101]
	s_add_u32 s100, s100, 0x10000
	s_addc_u32 s101, s101, 0
	v_pk_fma_f32 v[88:89], v[12:13], v[68:69], v[36:37] op_sel_hi:[1,0,1]
	s_waitcnt vmcnt(31)
	global_store_dwordx2 v4, v[88:89], s[100:101]
	s_add_u32 s100, s100, 0x10000
	s_addc_u32 s101, s101, 0
	v_pk_fma_f32 v[12:13], v[88:89], v[70:71], v[38:39] op_sel_hi:[1,0,1]
	global_load_dwordx2 v[24:25], v4, s[12:13]
	s_add_u32 s12, s12, 0x10000
	s_addc_u32 s13, s13, 0
	global_load_dword v56, v6, s[14:15] offset:0
	global_load_dwordx2 v[26:27], v4, s[12:13]
	s_add_u32 s12, s12, 0x10000
	s_addc_u32 s13, s13, 0
	global_load_dword v58, v6, s[14:15] offset:512
	global_load_dwordx2 v[28:29], v4, s[12:13]
	s_add_u32 s12, s12, 0x10000
	s_addc_u32 s13, s13, 0
	global_load_dword v60, v6, s[14:15] offset:1024
	global_load_dwordx2 v[30:31], v4, s[12:13]
	s_add_u32 s12, s12, 0x10000
	s_addc_u32 s13, s13, 0
	global_load_dword v62, v6, s[14:15] offset:1536
	global_load_dwordx2 v[32:33], v4, s[12:13]
	s_add_u32 s12, s12, 0x10000
	s_addc_u32 s13, s13, 0
	global_load_dword v64, v6, s[14:15] offset:2048
	global_load_dwordx2 v[34:35], v4, s[12:13]
	s_add_u32 s12, s12, 0x10000
	s_addc_u32 s13, s13, 0
	global_load_dword v66, v6, s[14:15] offset:2560
	global_load_dwordx2 v[36:37], v4, s[12:13]
	s_add_u32 s12, s12, 0x10000
	s_addc_u32 s13, s13, 0
	global_load_dword v68, v6, s[14:15] offset:3072
	global_load_dwordx2 v[38:39], v4, s[12:13]
	s_add_u32 s12, s12, 0x10000
	s_addc_u32 s13, s13, 0
	global_load_dword v70, v6, s[14:15] offset:3584
	s_add_u32 s14, s14, 0x1000
	s_addc_u32 s15, s15, 0
	s_waitcnt vmcnt(38)
	global_store_dwordx2 v4, v[12:13], s[100:101]
	s_add_u32 s100, s100, 0x10000
	s_addc_u32 s101, s101, 0
	v_pk_fma_f32 v[88:89], v[12:13], v[72:73], v[40:41] op_sel_hi:[1,0,1]
	s_waitcnt vmcnt(37)
; __device__ __forceinline__ void hgrn_h2(const int e) {
;     ...
;     for (int gid = bid * 512 + tid; gid < 16 * 128 * 64; gid += gsz * 512) {
;         const int bh = gid >> 13, k = (gid >> 6) & 127, v2 = (gid & 63) * 2;
;         f32x2h S = (f32x2h){0.f, 0.f};
;         float* ptr = LBUF + (size_t)bh * 64 * 16384 + (size_t)k * 128 + v2; const float* dp = DTOT + (size_t)bh * 64 * 128 + k;
; #pragma unroll 8
;         for (int c = 0; c < 64; ++c) { const f32x2h t = *(const f32x2h*)(ptr + (size_t)c * 16384); const float d = dp[c * 128]; *(f32x2h*)(ptr + (size_t)c * 16384) = S; S = S * d + t; }
	global_store_dwordx2 v4, v[88:89], s[100:101]
	s_add_u32 s100, s100, 0x10000
	s_addc_u32 s101, s101, 0
	v_pk_fma_f32 v[12:13], v[88:89], v[74:75], v[42:43] op_sel_hi:[1,0,1]
	s_waitcnt vmcnt(36)
	global_store_dwordx2 v4, v[12:13], s[100:101]
	s_add_u32 s100, s100, 0x10000
	s_addc_u32 s101, s101, 0
	v_pk_fma_f32 v[88:89], v[12:13], v[76:77], v[44:45] op_sel_hi:[1,0,1]
	s_waitcnt vmcnt(35)
	global_store_dwordx2 v4, v[88:89], s[100:101]
	s_add_u32 s100, s100, 0x10000
	s_addc_u32 s101, s101, 0
	v_pk_fma_f32 v[12:13], v[88:89], v[78:79], v[46:47] op_sel_hi:[1,0,1]
	s_waitcnt vmcnt(34)
	global_store_dwordx2 v4, v[12:13], s[100:101]
	s_add_u32 s100, s100, 0x10000
	s_addc_u32 s101, s101, 0
	v_pk_fma_f32 v[88:89], v[12:13], v[80:81], v[48:49] op_sel_hi:[1,0,1]
	s_waitcnt vmcnt(33)
	global_store_dwordx2 v4, v[88:89], s[100:101]
	s_add_u32 s100, s100, 0x10000
	s_addc_u32 s101, s101, 0
	v_pk_fma_f32 v[12:13], v[88:89], v[82:83], v[50:51] op_sel_hi:[1,0,1]
	s_waitcnt vmcnt(32)
	global_store_dwordx2 v4, v[12:13], s[100:101]
	s_add_u32 s100, s100, 0x10000
	s_addc_u32 s101, s101, 0
	v_pk_fma_f32 v[88:89], v[12:13], v[84:85], v[52:53] op_sel_hi:[1,0,1]
	s_waitcnt vmcnt(31)
	global_store_dwordx2 v4, v[88:89], s[100:101]
	s_add_u32 s100, s100, 0x10000
	s_addc_u32 s101, s101, 0
	v_pk_fma_f32 v[12:13], v[88:89], v[86:87], v[54:55] op_sel_hi:[1,0,1]
	global_load_dwordx2 v[40:41], v4, s[12:13]
	s_add_u32 s12, s12, 0x10000
	s_addc_u32 s13, s13, 0
	global_load_dword v72, v6, s[14:15] offset:0
	global_load_dwordx2 v[42:43], v4, s[12:13]
	s_add_u32 s12, s12, 0x10000
	s_addc_u32 s13, s13, 0
	global_load_dword v74, v6, s[14:15] offset:512
	global_load_dwordx2 v[44:45], v4, s[12:13]
	s_add_u32 s12, s12, 0x10000
	s_addc_u32 s13, s13, 0
	global_load_dword v76, v6, s[14:15] offset:1024
	global_load_dwordx2 v[46:47], v4, s[12:13]
	s_add_u32 s12, s12, 0x10000
	s_addc_u32 s13, s13, 0
	global_load_dword v78, v6, s[14:15] offset:1536
	global_load_dwordx2 v[48:49], v4, s[12:13]
	s_add_u32 s12, s12, 0x10000
	s_addc_u32 s13, s13, 0
	global_load_dword v80, v6, s[14:15] offset:2048
	global_load_dwordx2 v[50:51], v4, s[12:13]
	s_add_u32 s12, s12, 0x10000
	s_addc_u32 s13, s13, 0
	global_load_dword v82, v6, s[14:15] offset:2560
	global_load_dwordx2 v[52:53], v4, s[12:13]
	s_add_u32 s12, s12, 0x10000
	s_addc_u32 s13, s13, 0
	global_load_dword v84, v6, s[14:15] offset:3072
	global_load_dwordx2 v[54:55], v4, s[12:13]
	s_add_u32 s12, s12, 0x10000
	s_addc_u32 s13, s13, 0
	global_load_dword v86, v6, s[14:15] offset:3584
	s_add_u32 s14, s14, 0x1000
	s_addc_u32 s15, s15, 0
	s_waitcnt vmcnt(38)
	global_store_dwordx2 v4, v[12:13], s[100:101]
	s_add_u32 s100, s100, 0x10000
	s_addc_u32 s101, s101, 0
	v_pk_fma_f32 v[88:89], v[12:13], v[56:57], v[24:25] op_sel_hi:[1,0,1]
	s_waitcnt vmcnt(37)
	global_store_dwordx2 v4, v[88:89], s[100:101]
	s_add_u32 s100, s100, 0x10000
	s_addc_u32 s101, s101, 0
	v_pk_fma_f32 v[12:13], v[88:89], v[58:59], v[26:27] op_sel_hi:[1,0,1]
	s_waitcnt vmcnt(36)
	global_store_dwordx2 v4, v[12:13], s[100:101]
	s_add_u32 s100, s100, 0x10000
	s_addc_u32 s101, s101, 0
	v_pk_fma_f32 v[88:89], v[12:13], v[60:61], v[28:29] op_sel_hi:[1,0,1]
	s_waitcnt vmcnt(35)
	global_store_dwordx2 v4, v[88:89], s[100:101]
	s_add_u32 s100, s100, 0x10000
	s_addc_u32 s101, s101, 0
	v_pk_fma_f32 v[12:13], v[88:89], v[62:63], v[30:31] op_sel_hi:[1,0,1]
	s_waitcnt vmcnt(34)
	global_store_dwordx2 v4, v[12:13], s[100:101]
	s_add_u32 s100, s100, 0x10000
	s_addc_u32 s101, s101, 0
	v_pk_fma_f32 v[88:89], v[12:13], v[64:65], v[32:33] op_sel_hi:[1,0,1]
	s_waitcnt vmcnt(33)
	global_store_dwordx2 v4, v[88:89], s[100:101]
	s_add_u32 s100, s100, 0x10000
	s_addc_u32 s101, s101, 0
	v_pk_fma_f32 v[12:13], v[88:89], v[66:67], v[34:35] op_sel_hi:[1,0,1]
	s_waitcnt vmcnt(32)
	global_store_dwordx2 v4, v[12:13], s[100:101]
	s_add_u32 s100, s100, 0x10000
	s_addc_u32 s101, s101, 0
	v_pk_fma_f32 v[88:89], v[12:13], v[68:69], v[36:37] op_sel_hi:[1,0,1]
	s_waitcnt vmcnt(31)
	global_store_dwordx2 v4, v[88:89], s[100:101]
	s_add_u32 s100, s100, 0x10000
	s_addc_u32 s101, s101, 0
	v_pk_fma_f32 v[12:13], v[88:89], v[70:71], v[38:39] op_sel_hi:[1,0,1]
	global_load_dwordx2 v[24:25], v4, s[12:13]
	s_add_u32 s12, s12, 0x10000
	s_addc_u32 s13, s13, 0
	global_load_dword v56, v6, s[14:15] offset:0
	global_load_dwordx2 v[26:27], v4, s[12:13]
	s_add_u32 s12, s12, 0x10000
	s_addc_u32 s13, s13, 0
	global_load_dword v58, v6, s[14:15] offset:512
	global_load_dwordx2 v[28:29], v4, s[12:13]
	s_add_u32 s12, s12, 0x10000
	s_addc_u32 s13, s13, 0
	global_load_dword v60, v6, s[14:15] offset:1024
	global_load_dwordx2 v[30:31], v4, s[12:13]
	s_add_u32 s12, s12, 0x10000
	s_addc_u32 s13, s13, 0
	global_load_dword v62, v6, s[14:15] offset:1536
	global_load_dwordx2 v[32:33], v4, s[12:13]
	s_add_u32 s12, s12, 0x10000
	s_addc_u32 s13, s13, 0
	global_load_dword v64, v6, s[14:15] offset:2048
	global_load_dwordx2 v[34:35], v4, s[12:13]
	s_add_u32 s12, s12, 0x10000
	s_addc_u32 s13, s13, 0
	global_load_dword v66, v6, s[14:15] offset:2560
	global_load_dwordx2 v[36:37], v4, s[12:13]
	s_add_u32 s12, s12, 0x10000
	s_addc_u32 s13, s13, 0
	global_load_dword v68, v6, s[14:15] offset:3072
	global_load_dwordx2 v[38:39], v4, s[12:13]
	s_add_u32 s12, s12, 0x10000
	s_addc_u32 s13, s13, 0
	global_load_dword v70, v6, s[14:15] offset:3584
	s_add_u32 s14, s14, 0x1000
	s_addc_u32 s15, s15, 0
	s_waitcnt vmcnt(38)
	global_store_dwordx2 v4, v[12:13], s[100:101]
	s_add_u32 s100, s100, 0x10000
	s_addc_u32 s101, s101, 0
	v_pk_fma_f32 v[88:89], v[12:13], v[72:73], v[40:41] op_sel_hi:[1,0,1]
	s_waitcnt vmcnt(37)
; __device__ __forceinline__ float* OUTP() { return (float*)IN(40); }
; __device__ __forceinline__ void hgrn_h2(const int e) {
;     ...
;     for (int gid = bid * 512 + tid; gid < 16 * 128 * 64; gid += gsz * 512) {
;         const int bh = gid >> 13, k = (gid >> 6) & 127, v2 = (gid & 63) * 2;
;         f32x2h S = (f32x2h){0.f, 0.f};
;         float* ptr = LBUF + (size_t)bh * 64 * 16384 + (size_t)k * 128 + v2; const float* dp = DTOT + (size_t)bh * 64 * 128 + k;
; #pragma unroll 8
;         for (int c = 0; c < 64; ++c) { const f32x2h t = *(const f32x2h*)(ptr + (size_t)c * 16384); const float d = dp[c * 128]; *(f32x2h*)(ptr + (size_t)c * 16384) = S; S = S * d + t; }
;         *(f32x2h*)(OUTP() + OFF_HP + ((size_t)e * 16 + bh) * 16384 + (size_t)k * 128 + v2) = S;
;     }
	global_store_dwordx2 v4, v[88:89], s[100:101]
	s_add_u32 s100, s100, 0x10000
	s_addc_u32 s101, s101, 0
	v_pk_fma_f32 v[12:13], v[88:89], v[74:75], v[42:43] op_sel_hi:[1,0,1]
	s_waitcnt vmcnt(36)
	global_store_dwordx2 v4, v[12:13], s[100:101]
	s_add_u32 s100, s100, 0x10000
	s_addc_u32 s101, s101, 0
	v_pk_fma_f32 v[88:89], v[12:13], v[76:77], v[44:45] op_sel_hi:[1,0,1]
	s_waitcnt vmcnt(35)
	global_store_dwordx2 v4, v[88:89], s[100:101]
	s_add_u32 s100, s100, 0x10000
	s_addc_u32 s101, s101, 0
	v_pk_fma_f32 v[12:13], v[88:89], v[78:79], v[46:47] op_sel_hi:[1,0,1]
	s_waitcnt vmcnt(34)
	global_store_dwordx2 v4, v[12:13], s[100:101]
	s_add_u32 s100, s100, 0x10000
	s_addc_u32 s101, s101, 0
	v_pk_fma_f32 v[88:89], v[12:13], v[80:81], v[48:49] op_sel_hi:[1,0,1]
	s_waitcnt vmcnt(33)
	global_store_dwordx2 v4, v[88:89], s[100:101]
	s_add_u32 s100, s100, 0x10000
	s_addc_u32 s101, s101, 0
	v_pk_fma_f32 v[12:13], v[88:89], v[82:83], v[50:51] op_sel_hi:[1,0,1]
	s_waitcnt vmcnt(32)
	global_store_dwordx2 v4, v[12:13], s[100:101]
	s_add_u32 s100, s100, 0x10000
	s_addc_u32 s101, s101, 0
	v_pk_fma_f32 v[88:89], v[12:13], v[84:85], v[52:53] op_sel_hi:[1,0,1]
	s_waitcnt vmcnt(31)
	global_store_dwordx2 v4, v[88:89], s[100:101]
	s_add_u32 s100, s100, 0x10000
	s_addc_u32 s101, s101, 0
	v_pk_fma_f32 v[12:13], v[88:89], v[86:87], v[54:55] op_sel_hi:[1,0,1]
	global_load_dwordx2 v[40:41], v4, s[12:13]
	s_add_u32 s12, s12, 0x10000
	s_addc_u32 s13, s13, 0
	global_load_dword v72, v6, s[14:15] offset:0
	global_load_dwordx2 v[42:43], v4, s[12:13]
	s_add_u32 s12, s12, 0x10000
	s_addc_u32 s13, s13, 0
	global_load_dword v74, v6, s[14:15] offset:512
	global_load_dwordx2 v[44:45], v4, s[12:13]
	s_add_u32 s12, s12, 0x10000
	s_addc_u32 s13, s13, 0
	global_load_dword v76, v6, s[14:15] offset:1024
	global_load_dwordx2 v[46:47], v4, s[12:13]
	s_add_u32 s12, s12, 0x10000
	s_addc_u32 s13, s13, 0
	global_load_dword v78, v6, s[14:15] offset:1536
	global_load_dwordx2 v[48:49], v4, s[12:13]
	s_add_u32 s12, s12, 0x10000
	s_addc_u32 s13, s13, 0
	global_load_dword v80, v6, s[14:15] offset:2048
	global_load_dwordx2 v[50:51], v4, s[12:13]
	s_add_u32 s12, s12, 0x10000
	s_addc_u32 s13, s13, 0
	global_load_dword v82, v6, s[14:15] offset:2560
	global_load_dwordx2 v[52:53], v4, s[12:13]
	s_add_u32 s12, s12, 0x10000
	s_addc_u32 s13, s13, 0
	global_load_dword v84, v6, s[14:15] offset:3072
	global_load_dwordx2 v[54:55], v4, s[12:13]
	s_add_u32 s12, s12, 0x10000
	s_addc_u32 s13, s13, 0
	global_load_dword v86, v6, s[14:15] offset:3584
	s_add_u32 s14, s14, 0x1000
	s_addc_u32 s15, s15, 0
	s_waitcnt vmcnt(38)
	global_store_dwordx2 v4, v[12:13], s[100:101]
	s_add_u32 s100, s100, 0x10000
	s_addc_u32 s101, s101, 0
	v_pk_fma_f32 v[88:89], v[12:13], v[56:57], v[24:25] op_sel_hi:[1,0,1]
	s_waitcnt vmcnt(37)
	global_store_dwordx2 v4, v[88:89], s[100:101]
	s_add_u32 s100, s100, 0x10000
	s_addc_u32 s101, s101, 0
	v_pk_fma_f32 v[12:13], v[88:89], v[58:59], v[26:27] op_sel_hi:[1,0,1]
	s_waitcnt vmcnt(36)
	global_store_dwordx2 v4, v[12:13], s[100:101]
	s_add_u32 s100, s100, 0x10000
	s_addc_u32 s101, s101, 0
	v_pk_fma_f32 v[88:89], v[12:13], v[60:61], v[28:29] op_sel_hi:[1,0,1]
	s_waitcnt vmcnt(35)
	global_store_dwordx2 v4, v[88:89], s[100:101]
	s_add_u32 s100, s100, 0x10000
	s_addc_u32 s101, s101, 0
	v_pk_fma_f32 v[12:13], v[88:89], v[62:63], v[30:31] op_sel_hi:[1,0,1]
	s_waitcnt vmcnt(34)
	global_store_dwordx2 v4, v[12:13], s[100:101]
	s_add_u32 s100, s100, 0x10000
	s_addc_u32 s101, s101, 0
	v_pk_fma_f32 v[88:89], v[12:13], v[64:65], v[32:33] op_sel_hi:[1,0,1]
	s_waitcnt vmcnt(33)
	global_store_dwordx2 v4, v[88:89], s[100:101]
	s_add_u32 s100, s100, 0x10000
	s_addc_u32 s101, s101, 0
	v_pk_fma_f32 v[12:13], v[88:89], v[66:67], v[34:35] op_sel_hi:[1,0,1]
	s_waitcnt vmcnt(32)
	global_store_dwordx2 v4, v[12:13], s[100:101]
	s_add_u32 s100, s100, 0x10000
	s_addc_u32 s101, s101, 0
	v_pk_fma_f32 v[88:89], v[12:13], v[68:69], v[36:37] op_sel_hi:[1,0,1]
	s_waitcnt vmcnt(31)
	global_store_dwordx2 v4, v[88:89], s[100:101]
	s_add_u32 s100, s100, 0x10000
	s_addc_u32 s101, s101, 0
	v_pk_fma_f32 v[12:13], v[88:89], v[70:71], v[38:39] op_sel_hi:[1,0,1]
	s_waitcnt vmcnt(22)
	global_store_dwordx2 v4, v[12:13], s[100:101]
	s_add_u32 s100, s100, 0x10000
	s_addc_u32 s101, s101, 0
	v_pk_fma_f32 v[88:89], v[12:13], v[72:73], v[40:41] op_sel_hi:[1,0,1]
	s_waitcnt vmcnt(21)
	global_store_dwordx2 v4, v[88:89], s[100:101]
	s_add_u32 s100, s100, 0x10000
	s_addc_u32 s101, s101, 0
	v_pk_fma_f32 v[12:13], v[88:89], v[74:75], v[42:43] op_sel_hi:[1,0,1]
	s_waitcnt vmcnt(20)
	global_store_dwordx2 v4, v[12:13], s[100:101]
	s_add_u32 s100, s100, 0x10000
	s_addc_u32 s101, s101, 0
	v_pk_fma_f32 v[88:89], v[12:13], v[76:77], v[44:45] op_sel_hi:[1,0,1]
	s_waitcnt vmcnt(19)
	global_store_dwordx2 v4, v[88:89], s[100:101]
	s_add_u32 s100, s100, 0x10000
	s_addc_u32 s101, s101, 0
	v_pk_fma_f32 v[12:13], v[88:89], v[78:79], v[46:47] op_sel_hi:[1,0,1]
	s_waitcnt vmcnt(18)
	global_store_dwordx2 v4, v[12:13], s[100:101]
	s_add_u32 s100, s100, 0x10000
	s_addc_u32 s101, s101, 0
	v_pk_fma_f32 v[88:89], v[12:13], v[80:81], v[48:49] op_sel_hi:[1,0,1]
	s_waitcnt vmcnt(17)
	global_store_dwordx2 v4, v[88:89], s[100:101]
	s_add_u32 s100, s100, 0x10000
	s_addc_u32 s101, s101, 0
	v_pk_fma_f32 v[12:13], v[88:89], v[82:83], v[50:51] op_sel_hi:[1,0,1]
	s_waitcnt vmcnt(16)
	global_store_dwordx2 v4, v[12:13], s[100:101]
	s_add_u32 s100, s100, 0x10000
	s_addc_u32 s101, s101, 0
	v_pk_fma_f32 v[88:89], v[12:13], v[84:85], v[52:53] op_sel_hi:[1,0,1]
	s_waitcnt vmcnt(15)
	global_store_dwordx2 v4, v[88:89], s[100:101]
	s_add_u32 s100, s100, 0x10000
	s_addc_u32 s101, s101, 0
	v_pk_fma_f32 v[12:13], v[88:89], v[86:87], v[54:55] op_sel_hi:[1,0,1]
	s_movk_i32 s12, 0x140
	s_ashr_i32 s13, s12, 31
	s_add_u32 s12, s0, s12
	s_addc_u32 s13, s1, s13
	s_load_dwordx2 s[12:13], s[12:13], 0x0
	v_readlane_b32 s14, v234, 40
	v_and_b32_e32 v2, 0x7f, v2
	v_lshlrev_b64 v[0:1], 16, v[0:1]
	v_lshlrev_b32_e32 v2, 9, v2
	s_waitcnt lgkmcnt(0)
	s_add_u32 s12, s12, s14
	s_addc_u32 s13, s13, 0
	v_lshl_add_u64 v[0:1], s[12:13], 0, v[0:1]
	v_lshl_add_u64 v[0:1], v[0:1], 0, v[2:3]
	v_and_b32_e32 v2, 0x1f8, v16
	v_lshl_add_u64 v[0:1], v[0:1], 0, v[2:3]
	v_add_co_u32_e32 v0, vcc, 0x4200000, v0
	v_add_u32_e32 v14, s4, v14
	s_nop 0
	v_addc_co_u32_e32 v1, vcc, 0, v1, vcc
	s_mov_b32 s12, 0x1ffff
	v_cmp_lt_i32_e32 vcc, s12, v14
	s_or_b64 s[10:11], vcc, s[10:11]
	v_add_u32_e32 v15, s5, v15
	global_store_dwordx2 v[0:1], v[12:13], off
	s_andn2_b64 exec, exec, s[10:11]
	s_cbranch_execnz .LBB0_892

; #define LAS __attribute__((address_space(3)))
; __global__ void __launch_bounds__(512, 2) mega_fwd(Params p) {
;     extern __shared__ __attribute__((aligned(16))) unsigned char lds_raw[];
;     LAS unsigned char* lds = (LAS unsigned char*)lds_raw;
;     cg::grid_group grid = cg::this_grid();
	.amdhsa_kernel _Z8mega_fwd6Params
		.amdhsa_group_segment_fixed_size 0
		.amdhsa_private_segment_fixed_size 0
		.amdhsa_kernarg_size 592
		.amdhsa_user_sgpr_count 2
		.amdhsa_user_sgpr_dispatch_ptr 0
		.amdhsa_user_sgpr_queue_ptr 0
		.amdhsa_user_sgpr_kernarg_segment_ptr 1
		.amdhsa_user_sgpr_dispatch_id 0
		.amdhsa_user_sgpr_kernarg_preload_length 0
		.amdhsa_user_sgpr_kernarg_preload_offset 0
		.amdhsa_user_sgpr_private_segment_size 0
		.amdhsa_uses_dynamic_stack 0
		.amdhsa_enable_private_segment 0
		.amdhsa_system_sgpr_workgroup_id_x 1
		.amdhsa_system_sgpr_workgroup_id_y 0
		.amdhsa_system_sgpr_workgroup_id_z 0
		.amdhsa_system_sgpr_workgroup_info 0
		.amdhsa_system_vgpr_workitem_id 2
		.amdhsa_next_free_vgpr 236
		.amdhsa_next_free_sgpr 102
		.amdhsa_accum_offset 236
		.amdhsa_reserve_vcc 1
		.amdhsa_float_round_mode_32 0
		.amdhsa_float_round_mode_16_64 0
		.amdhsa_float_denorm_mode_32 3
		.amdhsa_float_denorm_mode_16_64 3
		.amdhsa_dx10_clamp 1
		.amdhsa_ieee_mode 1
		.amdhsa_fp16_overflow 0
		.amdhsa_tg_split 0
		.amdhsa_exception_fp_ieee_invalid_op 0
		.amdhsa_exception_fp_denorm_src 0
		.amdhsa_exception_fp_ieee_div_zero 0
		.amdhsa_exception_fp_ieee_overflow 0
		.amdhsa_exception_fp_ieee_underflow 0
		.amdhsa_exception_fp_ieee_inexact 0
		.amdhsa_exception_int_div_zero 0
	.end_amdhsa_kernel

; #define LAS __attribute__((address_space(3)))
; __global__ void __launch_bounds__(512, 2) mega_fwd(Params p) {
;     extern __shared__ __attribute__((aligned(16))) unsigned char lds_raw[];
;     LAS unsigned char* lds = (LAS unsigned char*)lds_raw;
;     cg::grid_group grid = cg::this_grid();
amdhsa.kernels:
  - .agpr_count:     0
    .args:
      - .offset:         0
        .size:           336
        .value_kind:     by_value
      - .offset:         336
        .size:           4
        .value_kind:     hidden_block_count_x
      - .offset:         340
        .size:           4
        .value_kind:     hidden_block_count_y
      - .offset:         344
        .size:           4
        .value_kind:     hidden_block_count_z
      - .offset:         348
        .size:           2
        .value_kind:     hidden_group_size_x
      - .offset:         350
        .size:           2
        .value_kind:     hidden_group_size_y
      - .offset:         352
        .size:           2
        .value_kind:     hidden_group_size_z
      - .offset:         354
        .size:           2
        .value_kind:     hidden_remainder_x
      - .offset:         356
        .size:           2
        .value_kind:     hidden_remainder_y
      - .offset:         358
        .size:           2
        .value_kind:     hidden_remainder_z
      - .offset:         376
        .size:           8
        .value_kind:     hidden_global_offset_x
      - .offset:         384
        .size:           8
        .value_kind:     hidden_global_offset_y
      - .offset:         392
        .size:           8
        .value_kind:     hidden_global_offset_z
      - .offset:         400
        .size:           2
        .value_kind:     hidden_grid_dims
      - .offset:         424
        .size:           8
        .value_kind:     hidden_multigrid_sync_arg
      - .offset:         456
        .size:           4
        .value_kind:     hidden_dynamic_lds_size
    .group_segment_fixed_size: 0
    .kernarg_segment_align: 8
    .kernarg_segment_size: 592
    .language:       OpenCL C
    .language_version:
      - 2
      - 0
    .max_flat_workgroup_size: 512
    .name:           _Z8mega_fwd6Params
    .private_segment_fixed_size: 0
    .sgpr_count:     108
    .sgpr_spill_count: 130
    .symbol:         _Z8mega_fwd6Params.kd
    .uniform_work_group_size: 1
    .uses_dynamic_stack: false
    .vgpr_count:     236
    .vgpr_spill_count: 0
    .wavefront_size: 64
